# v84 + in-proj epilogue row-scale loads hoisted to tile start (no load round trip at each P1 tile end)
# baseline (speedup 1.0000x reference)
.LBB0_228:
	s_ashr_i32 s39, s38, 31
	s_lshl_b64 s[40:41], s[38:39], 19
	v_readlane_b32 s42, v238, 7
	v_readlane_b32 s43, v238, 8
	s_add_u32 s40, s42, s40
	s_addc_u32 s41, s43, s41
	s_and_b64 s[42:43], s[2:3], exec
	s_cselect_b32 s5, s41, s1
	s_cselect_b32 s7, s40, s0
	s_ashr_i32 s37, s36, 31
	s_lshl_b64 s[42:43], s[36:37], 19
	s_add_u32 s42, s64, s42
	s_addc_u32 s43, s65, s43
	s_and_b64 s[44:45], s[2:3], exec
	s_cselect_b32 s33, s43, s9
	s_cselect_b32 s37, s42, s8
	s_add_u32 s0, s0, 0x40080
	s_addc_u32 s1, s1, 0
	s_add_u32 s39, s8, 0x100
	s_addc_u32 s46, s9, 0
	s_mov_b32 s47, -2
	v_lshl_add_u32 v248, s6, 8, v167
	v_ashrrev_i32_e32 v249, 31, v248
	v_lshl_add_u64 v[248:249], v[248:249], 2, s[10:11]
	global_load_dword v240, v[248:249], off
	global_load_dword v241, v[248:249], off offset:64
	global_load_dword v242, v[248:249], off offset:128
	global_load_dword v243, v[248:249], off offset:192
	global_load_dword v244, v[248:249], off offset:512
	global_load_dword v245, v[248:249], off offset:576
	global_load_dword v246, v[248:249], off offset:640
	global_load_dword v247, v[248:249], off offset:704
	ds_read_b128 v[144:147], v170
	ds_read_b128 v[148:151], v170 offset:1024
	ds_read_b128 v[152:155], v170 offset:2048
	ds_read_b128 v[156:159], v170 offset:3072
	ds_read_b128 v[162:165], v171
	ds_read_b128 v[174:177], v171 offset:1024
	ds_read_b128 v[178:181], v171 offset:2048
	ds_read_b128 v[182:185], v171 offset:3072
	s_add_u32 s8, s0, 0xfffc0080
	s_addc_u32 s9, s1, -1
	s_cmp_eq_u32 s47, 12
	s_cselect_b32 s45, s5, s9
	s_cselect_b32 s44, s7, s8
	s_cselect_b32 s9, s33, s46
	s_cselect_b32 s8, s37, s39
	v_lshl_add_u64 v[218:219], s[0:1], 0, v[136:137]
	s_add_i32 m0, s67, 0xc000
	ds_read_b128 v[186:189], v172
	ds_read_b128 v[190:193], v172 offset:1024
	ds_read_b128 v[194:197], v172 offset:2048
	ds_read_b128 v[198:201], v172 offset:3072
	ds_read_b128 v[202:205], v172 offset:4096
	ds_read_b128 v[206:209], v172 offset:5120
	ds_read_b128 v[210:213], v172 offset:6144
	ds_read_b128 v[214:217], v172 offset:7168
	global_load_lds_dwordx4 v[218:219], off
	s_add_i32 m0, s67, 0xe000
	v_lshl_add_u64 v[218:219], s[0:1], 0, v[138:139]
	global_load_lds_dwordx4 v[218:219], off
	s_waitcnt vmcnt(8) lgkmcnt(0)
	s_barrier
	v_mfma_f32_16x16x32_bf16 v[124:127], v[144:147], v[186:189], 0
	v_mfma_f32_16x16x32_bf16 v[120:123], v[152:155], v[186:189], 0
	v_mfma_f32_16x16x32_bf16 v[108:111], v[144:147], v[194:197], 0
	v_mfma_f32_16x16x32_bf16 v[104:107], v[152:155], v[194:197], 0
	v_mfma_f32_16x16x32_bf16 v[92:95], v[144:147], v[202:205], 0
	v_mfma_f32_16x16x32_bf16 v[88:91], v[152:155], v[202:205], 0
	v_mfma_f32_16x16x32_bf16 v[76:79], v[144:147], v[210:213], 0
	v_mfma_f32_16x16x32_bf16 v[72:75], v[152:155], v[210:213], 0
	v_mfma_f32_16x16x32_bf16 v[124:127], v[148:151], v[190:193], v[124:127]
	v_mfma_f32_16x16x32_bf16 v[120:123], v[156:159], v[190:193], v[120:123]
	v_mfma_f32_16x16x32_bf16 v[108:111], v[148:151], v[198:201], v[108:111]
	v_mfma_f32_16x16x32_bf16 v[104:107], v[156:159], v[198:201], v[104:107]
	v_mfma_f32_16x16x32_bf16 v[92:95], v[148:151], v[206:209], v[92:95]
	v_mfma_f32_16x16x32_bf16 v[88:91], v[156:159], v[206:209], v[88:91]
	v_mfma_f32_16x16x32_bf16 v[76:79], v[148:151], v[214:217], v[76:79]
	v_mfma_f32_16x16x32_bf16 v[72:75], v[156:159], v[214:217], v[72:75]
	v_mfma_f32_16x16x32_bf16 v[116:119], v[162:165], v[186:189], 0
	v_mfma_f32_16x16x32_bf16 v[112:115], v[178:181], v[186:189], 0
	v_mfma_f32_16x16x32_bf16 v[100:103], v[162:165], v[194:197], 0
	v_mfma_f32_16x16x32_bf16 v[96:99], v[178:181], v[194:197], 0
	v_mfma_f32_16x16x32_bf16 v[84:87], v[162:165], v[202:205], 0
	v_mfma_f32_16x16x32_bf16 v[80:83], v[178:181], v[202:205], 0
	v_mfma_f32_16x16x32_bf16 v[68:71], v[162:165], v[210:213], 0
	v_mfma_f32_16x16x32_bf16 v[64:67], v[178:181], v[210:213], 0
	v_mfma_f32_16x16x32_bf16 v[116:119], v[174:177], v[190:193], v[116:119]
	v_mfma_f32_16x16x32_bf16 v[112:115], v[182:185], v[190:193], v[112:115]
	v_mfma_f32_16x16x32_bf16 v[100:103], v[174:177], v[198:201], v[100:103]
	v_mfma_f32_16x16x32_bf16 v[96:99], v[182:185], v[198:201], v[96:99]
	v_mfma_f32_16x16x32_bf16 v[84:87], v[174:177], v[206:209], v[84:87]
	v_mfma_f32_16x16x32_bf16 v[80:83], v[182:185], v[206:209], v[80:83]
	v_mfma_f32_16x16x32_bf16 v[68:71], v[174:177], v[214:217], v[68:71]
	v_mfma_f32_16x16x32_bf16 v[64:67], v[182:185], v[214:217], v[64:67]
	s_barrier
	s_add_i32 s52, s79, s66
	v_lshl_add_u64 v[218:219], s[8:9], 0, v[130:131]
	s_mov_b32 m0, s52
	ds_read_b128 v[186:189], v172 offset:16384
	ds_read_b128 v[190:193], v172 offset:17408
	ds_read_b128 v[194:197], v172 offset:18432
	ds_read_b128 v[198:201], v172 offset:19456
	ds_read_b128 v[202:205], v172 offset:20480
	ds_read_b128 v[206:209], v172 offset:21504
	ds_read_b128 v[210:213], v172 offset:22528
	ds_read_b128 v[214:217], v172 offset:23552
	global_load_lds_dwordx4 v[218:219], off
	s_add_i32 m0, s52, 0x2000
	s_add_u32 s52, s8, 0x40000
	v_lshl_add_u64 v[220:221], s[8:9], 0, v[134:135]
	s_addc_u32 s53, s9, 0
	s_add_i32 s56, s85, s66
	global_load_lds_dwordx4 v[220:221], off
	v_lshl_add_u64 v[222:223], s[52:53], 0, v[130:131]
	s_mov_b32 m0, s56
	v_lshl_add_u64 v[224:225], s[44:45], 0, v[132:133]
	global_load_lds_dwordx4 v[222:223], off
	s_add_i32 m0, s56, 0x2000
	v_lshl_add_u64 v[222:223], s[52:53], 0, v[134:135]
	global_load_lds_dwordx4 v[222:223], off
	s_mov_b32 m0, s67
	v_lshl_add_u64 v[222:223], s[44:45], 0, v[128:129]
	global_load_lds_dwordx4 v[222:223], off
	s_mov_b32 m0, s72
	s_nop 0
	global_load_lds_dwordx4 v[224:225], off
	s_waitcnt vmcnt(8) lgkmcnt(0)
	s_barrier
	v_mfma_f32_16x16x32_bf16 v[60:63], v[144:147], v[186:189], 0
	v_mfma_f32_16x16x32_bf16 v[56:59], v[152:155], v[186:189], 0
	v_mfma_f32_16x16x32_bf16 v[44:47], v[144:147], v[194:197], 0
	v_mfma_f32_16x16x32_bf16 v[40:43], v[152:155], v[194:197], 0
	v_mfma_f32_16x16x32_bf16 v[28:31], v[144:147], v[202:205], 0
	v_mfma_f32_16x16x32_bf16 v[24:27], v[152:155], v[202:205], 0
	v_mfma_f32_16x16x32_bf16 v[12:15], v[144:147], v[210:213], 0
	v_mfma_f32_16x16x32_bf16 v[8:11], v[152:155], v[210:213], 0
	v_mfma_f32_16x16x32_bf16 v[60:63], v[148:151], v[190:193], v[60:63]
	v_mfma_f32_16x16x32_bf16 v[56:59], v[156:159], v[190:193], v[56:59]
	v_mfma_f32_16x16x32_bf16 v[44:47], v[148:151], v[198:201], v[44:47]
	v_mfma_f32_16x16x32_bf16 v[40:43], v[156:159], v[198:201], v[40:43]
	v_mfma_f32_16x16x32_bf16 v[28:31], v[148:151], v[206:209], v[28:31]
	v_mfma_f32_16x16x32_bf16 v[24:27], v[156:159], v[206:209], v[24:27]
	v_mfma_f32_16x16x32_bf16 v[12:15], v[148:151], v[214:217], v[12:15]
	v_mfma_f32_16x16x32_bf16 v[8:11], v[156:159], v[214:217], v[8:11]
	v_mfma_f32_16x16x32_bf16 v[52:55], v[162:165], v[186:189], 0
	v_mfma_f32_16x16x32_bf16 v[48:51], v[178:181], v[186:189], 0
	v_mfma_f32_16x16x32_bf16 v[36:39], v[162:165], v[194:197], 0
	v_mfma_f32_16x16x32_bf16 v[32:35], v[178:181], v[194:197], 0
	v_mfma_f32_16x16x32_bf16 v[20:23], v[162:165], v[202:205], 0
	v_mfma_f32_16x16x32_bf16 v[16:19], v[178:181], v[202:205], 0
	v_mfma_f32_16x16x32_bf16 v[4:7], v[162:165], v[210:213], 0
	v_mfma_f32_16x16x32_bf16 v[0:3], v[178:181], v[210:213], 0
	v_mfma_f32_16x16x32_bf16 v[52:55], v[174:177], v[190:193], v[52:55]
	v_mfma_f32_16x16x32_bf16 v[48:51], v[182:185], v[190:193], v[48:51]
	v_mfma_f32_16x16x32_bf16 v[36:39], v[174:177], v[198:201], v[36:39]
	v_mfma_f32_16x16x32_bf16 v[32:35], v[182:185], v[198:201], v[32:35]
	v_mfma_f32_16x16x32_bf16 v[20:23], v[174:177], v[206:209], v[20:23]
	v_mfma_f32_16x16x32_bf16 v[16:19], v[182:185], v[206:209], v[16:19]
	v_mfma_f32_16x16x32_bf16 v[4:7], v[174:177], v[214:217], v[4:7]
	v_mfma_f32_16x16x32_bf16 v[0:3], v[182:185], v[214:217], v[0:3]
	s_barrier
	s_add_i32 s52, 0, 0x18000
	s_add_i32 s53, 0, 0x1c000
	v_add_u32_e32 v156, s52, v168
	v_add_u32_e32 v173, s53, v168
	ds_read_b128 v[144:147], v156
	ds_read_b128 v[148:151], v156 offset:1024
	ds_read_b128 v[152:155], v156 offset:2048
	ds_read_b128 v[156:159], v156 offset:3072
	ds_read_b128 v[162:165], v173
	ds_read_b128 v[174:177], v173 offset:1024
	ds_read_b128 v[178:181], v173 offset:2048
	ds_read_b128 v[182:185], v173 offset:3072
	s_add_u32 s44, s44, 0x40000
	s_addc_u32 s45, s45, 0
	s_mov_b32 m0, s73
	v_lshl_add_u64 v[226:227], s[44:45], 0, v[128:129]
	ds_read_b128 v[186:189], v172 offset:32768
	ds_read_b128 v[190:193], v172 offset:33792
	ds_read_b128 v[194:197], v172 offset:34816
	ds_read_b128 v[198:201], v172 offset:35840
	ds_read_b128 v[202:205], v172 offset:36864
	ds_read_b128 v[206:209], v172 offset:37888
	ds_read_b128 v[210:213], v172 offset:38912
	ds_read_b128 v[214:217], v172 offset:39936
	global_load_lds_dwordx4 v[226:227], off
	s_mov_b32 m0, s74
	v_lshl_add_u64 v[226:227], s[44:45], 0, v[132:133]
	global_load_lds_dwordx4 v[226:227], off
	s_waitcnt vmcnt(8) lgkmcnt(0)
	s_barrier
	v_mfma_f32_16x16x32_bf16 v[124:127], v[144:147], v[186:189], v[124:127]
	v_mfma_f32_16x16x32_bf16 v[120:123], v[152:155], v[186:189], v[120:123]
	v_mfma_f32_16x16x32_bf16 v[108:111], v[144:147], v[194:197], v[108:111]
	v_mfma_f32_16x16x32_bf16 v[104:107], v[152:155], v[194:197], v[104:107]
	v_mfma_f32_16x16x32_bf16 v[92:95], v[144:147], v[202:205], v[92:95]
	v_mfma_f32_16x16x32_bf16 v[88:91], v[152:155], v[202:205], v[88:91]
	v_mfma_f32_16x16x32_bf16 v[76:79], v[144:147], v[210:213], v[76:79]
	v_mfma_f32_16x16x32_bf16 v[72:75], v[152:155], v[210:213], v[72:75]
	v_mfma_f32_16x16x32_bf16 v[124:127], v[148:151], v[190:193], v[124:127]
	v_mfma_f32_16x16x32_bf16 v[120:123], v[156:159], v[190:193], v[120:123]
	v_mfma_f32_16x16x32_bf16 v[108:111], v[148:151], v[198:201], v[108:111]
	v_mfma_f32_16x16x32_bf16 v[104:107], v[156:159], v[198:201], v[104:107]
	v_mfma_f32_16x16x32_bf16 v[92:95], v[148:151], v[206:209], v[92:95]
	v_mfma_f32_16x16x32_bf16 v[88:91], v[156:159], v[206:209], v[88:91]
	v_mfma_f32_16x16x32_bf16 v[76:79], v[148:151], v[214:217], v[76:79]
	v_mfma_f32_16x16x32_bf16 v[72:75], v[156:159], v[214:217], v[72:75]
	v_mfma_f32_16x16x32_bf16 v[116:119], v[162:165], v[186:189], v[116:119]
	v_mfma_f32_16x16x32_bf16 v[112:115], v[178:181], v[186:189], v[112:115]
	v_mfma_f32_16x16x32_bf16 v[100:103], v[162:165], v[194:197], v[100:103]
	v_mfma_f32_16x16x32_bf16 v[96:99], v[178:181], v[194:197], v[96:99]
	v_mfma_f32_16x16x32_bf16 v[84:87], v[162:165], v[202:205], v[84:87]
	v_mfma_f32_16x16x32_bf16 v[80:83], v[178:181], v[202:205], v[80:83]
	v_mfma_f32_16x16x32_bf16 v[68:71], v[162:165], v[210:213], v[68:71]
	v_mfma_f32_16x16x32_bf16 v[64:67], v[178:181], v[210:213], v[64:67]
	v_mfma_f32_16x16x32_bf16 v[116:119], v[174:177], v[190:193], v[116:119]
	v_mfma_f32_16x16x32_bf16 v[112:115], v[182:185], v[190:193], v[112:115]
	v_mfma_f32_16x16x32_bf16 v[100:103], v[174:177], v[198:201], v[100:103]
	v_mfma_f32_16x16x32_bf16 v[96:99], v[182:185], v[198:201], v[96:99]
	v_mfma_f32_16x16x32_bf16 v[84:87], v[174:177], v[206:209], v[84:87]
	v_mfma_f32_16x16x32_bf16 v[80:83], v[182:185], v[206:209], v[80:83]
	v_mfma_f32_16x16x32_bf16 v[68:71], v[174:177], v[214:217], v[68:71]
	v_mfma_f32_16x16x32_bf16 v[64:67], v[182:185], v[214:217], v[64:67]
	s_barrier
	s_add_i32 s44, s52, s66
	v_lshl_add_u64 v[218:219], v[218:219], 0, s[30:31]
	s_mov_b32 m0, s44
	ds_read_b128 v[186:189], v172 offset:49152
	ds_read_b128 v[190:193], v172 offset:50176
	ds_read_b128 v[194:197], v172 offset:51200
	ds_read_b128 v[198:201], v172 offset:52224
	ds_read_b128 v[202:205], v172 offset:53248
	ds_read_b128 v[206:209], v172 offset:54272
	ds_read_b128 v[210:213], v172 offset:55296
	ds_read_b128 v[214:217], v172 offset:56320
	global_load_lds_dwordx4 v[218:219], off
	s_add_i32 m0, s44, 0x2000
	s_add_u32 s8, s8, 0x40080
	v_lshl_add_u64 v[218:219], v[220:221], 0, s[30:31]
	s_addc_u32 s9, s9, 0
	s_add_i32 s44, s53, s66
	global_load_lds_dwordx4 v[218:219], off
	s_mov_b32 m0, s44
	v_lshl_add_u64 v[218:219], s[8:9], 0, v[130:131]
	global_load_lds_dwordx4 v[218:219], off
	s_add_i32 m0, s44, 0x2000
	v_lshl_add_u64 v[218:219], s[8:9], 0, v[134:135]
	global_load_lds_dwordx4 v[218:219], off
	s_mov_b32 m0, s77
	v_lshl_add_u64 v[218:219], v[222:223], 0, s[30:31]
	global_load_lds_dwordx4 v[218:219], off
	s_mov_b32 m0, s78
	v_lshl_add_u64 v[218:219], v[224:225], 0, s[30:31]
	global_load_lds_dwordx4 v[218:219], off
	s_waitcnt vmcnt(8) lgkmcnt(0)
	s_barrier
	v_mfma_f32_16x16x32_bf16 v[60:63], v[144:147], v[186:189], v[60:63]
	v_mfma_f32_16x16x32_bf16 v[56:59], v[152:155], v[186:189], v[56:59]
	v_mfma_f32_16x16x32_bf16 v[44:47], v[144:147], v[194:197], v[44:47]
	v_mfma_f32_16x16x32_bf16 v[40:43], v[152:155], v[194:197], v[40:43]
	v_mfma_f32_16x16x32_bf16 v[28:31], v[144:147], v[202:205], v[28:31]
	v_mfma_f32_16x16x32_bf16 v[24:27], v[152:155], v[202:205], v[24:27]
	v_mfma_f32_16x16x32_bf16 v[12:15], v[144:147], v[210:213], v[12:15]
	v_mfma_f32_16x16x32_bf16 v[8:11], v[152:155], v[210:213], v[8:11]
	v_mfma_f32_16x16x32_bf16 v[60:63], v[148:151], v[190:193], v[60:63]
	v_mfma_f32_16x16x32_bf16 v[56:59], v[156:159], v[190:193], v[56:59]
	v_mfma_f32_16x16x32_bf16 v[44:47], v[148:151], v[198:201], v[44:47]
	v_mfma_f32_16x16x32_bf16 v[40:43], v[156:159], v[198:201], v[40:43]
	v_mfma_f32_16x16x32_bf16 v[28:31], v[148:151], v[206:209], v[28:31]
	v_mfma_f32_16x16x32_bf16 v[24:27], v[156:159], v[206:209], v[24:27]
	v_mfma_f32_16x16x32_bf16 v[12:15], v[148:151], v[214:217], v[12:15]
	v_mfma_f32_16x16x32_bf16 v[8:11], v[156:159], v[214:217], v[8:11]
	v_mfma_f32_16x16x32_bf16 v[52:55], v[162:165], v[186:189], v[52:55]
	v_mfma_f32_16x16x32_bf16 v[48:51], v[178:181], v[186:189], v[48:51]
	v_mfma_f32_16x16x32_bf16 v[36:39], v[162:165], v[194:197], v[36:39]
	v_mfma_f32_16x16x32_bf16 v[32:35], v[178:181], v[194:197], v[32:35]
	v_mfma_f32_16x16x32_bf16 v[20:23], v[162:165], v[202:205], v[20:23]
	v_mfma_f32_16x16x32_bf16 v[16:19], v[178:181], v[202:205], v[16:19]
	v_mfma_f32_16x16x32_bf16 v[4:7], v[162:165], v[210:213], v[4:7]
	v_mfma_f32_16x16x32_bf16 v[0:3], v[178:181], v[210:213], v[0:3]
	v_mfma_f32_16x16x32_bf16 v[52:55], v[174:177], v[190:193], v[52:55]
	v_mfma_f32_16x16x32_bf16 v[48:51], v[182:185], v[190:193], v[48:51]
	v_mfma_f32_16x16x32_bf16 v[36:39], v[174:177], v[198:201], v[36:39]
	v_mfma_f32_16x16x32_bf16 v[32:35], v[182:185], v[198:201], v[32:35]
	v_mfma_f32_16x16x32_bf16 v[20:23], v[174:177], v[206:209], v[20:23]
	v_mfma_f32_16x16x32_bf16 v[16:19], v[182:185], v[206:209], v[16:19]
	v_mfma_f32_16x16x32_bf16 v[4:7], v[174:177], v[214:217], v[4:7]
	v_mfma_f32_16x16x32_bf16 v[0:3], v[182:185], v[214:217], v[0:3]
	s_barrier
	s_add_i32 s47, s47, 2
	s_add_u32 s0, s0, 0x100
	s_addc_u32 s1, s1, 0
	s_add_u32 s39, s39, 0x100
	s_addc_u32 s46, s46, 0
	s_cmp_gt_u32 s47, 13
	s_cbranch_scc0 .LBB0_229
	s_branch .Lpeel_exit_1

.LBB0_232:
	s_cmp_lt_i32 s4, 5
	s_cselect_b64 s[44:45], -1, 0
	s_cmp_gt_i32 s4, 4
	s_cselect_b64 s[8:9], -1, 0
	s_lshl_b32 s37, s6, 8
	v_add_u32_e32 v144, s37, v167
	v_add_u32_e32 v150, 0x90, v144
	v_ashrrev_i32_e32 v145, 31, v144
	v_ashrrev_i32_e32 v151, 31, v150
	v_lshl_add_u64 v[146:147], v[144:145], 2, s[10:11]
	v_add_u32_e32 v148, 0x80, v144
	v_lshl_add_u64 v[162:163], v[150:151], 2, s[10:11]
	v_add_u32_e32 v150, 0xa0, v144
	v_add_u32_e32 v144, 0xb0, v144
	v_ashrrev_i32_e32 v149, 31, v148
	v_ashrrev_i32_e32 v145, 31, v144
	v_lshl_add_u64 v[148:149], v[148:149], 2, s[10:11]
	v_ashrrev_i32_e32 v151, 31, v150
	v_lshl_add_u64 v[144:145], v[144:145], 2, s[10:11]
	v_lshl_add_u64 v[164:165], v[150:151], 2, s[10:11]
	v_mov_b32_e32 v158, v240
	v_mov_b32_e32 v156, v241
	v_mov_b32_e32 v154, v242
	v_mov_b32_e32 v152, v243
	v_mov_b32_e32 v150, v244
	s_nop 0
	v_mov_b32_e32 v148, v245
	v_mov_b32_e32 v146, v246
	s_nop 0
	v_mov_b32_e32 v144, v247
	s_and_b64 vcc, exec, s[8:9]
	v_pk_mul_f32 v[126:127], v[126:127], v[158:159] op_sel_hi:[1,0]
	v_pk_mul_f32 v[162:163], v[124:125], v[158:159] op_sel_hi:[1,0]
	v_pk_mul_f32 v[124:125], v[122:123], v[158:159] op_sel_hi:[1,0]
	v_pk_mul_f32 v[164:165], v[120:121], v[158:159] op_sel_hi:[1,0]
	s_cbranch_vccnz .LBB0_234
	v_mul_f32_e32 v121, 0x3d372713, v164
	v_mul_f32_e32 v121, v164, v121
	v_mul_f32_e32 v122, 0x3d372713, v163
	v_fma_f32 v121, v164, v121, v164
	v_mul_f32_e32 v122, v163, v122
	v_mov_b32_e32 v123, v163
	v_mul_f32_e32 v121, 0x3f4c422a, v121
	v_fmac_f32_e32 v123, v123, v122
	v_mul_f32_e32 v121, 0xc038aa3b, v121
	v_mul_f32_e32 v122, 0x3f4c422a, v123
	v_exp_f32_e32 v121, v121
	v_mul_f32_e32 v122, 0xc038aa3b, v122
	v_exp_f32_e32 v123, v122
	v_mov_b32_e32 v145, v165
	v_add_f32_e32 v121, 1.0, v121
	v_rcp_f32_e32 v122, v121
	v_add_f32_e32 v121, 1.0, v123
	v_mul_f32_e32 v123, 0x3d372713, v165
	v_mul_f32_e32 v123, v165, v123
	v_fmac_f32_e32 v145, v145, v123
	v_mul_f32_e32 v123, 0x3f4c422a, v145
	v_mul_f32_e32 v145, 0x3d372713, v126
	v_mul_f32_e32 v145, v126, v145
	v_mul_f32_e32 v147, 0x3d372713, v124
	v_fma_f32 v145, v126, v145, v126
	v_mul_f32_e32 v147, v124, v147
	v_mul_f32_e32 v145, 0x3f4c422a, v145
	v_fma_f32 v147, v124, v147, v124
	v_mul_f32_e32 v145, 0xc038aa3b, v145
	v_mul_f32_e32 v147, 0x3f4c422a, v147
	v_exp_f32_e32 v145, v145
	v_mul_f32_e32 v147, 0xc038aa3b, v147
	v_exp_f32_e32 v147, v147
	v_mul_f32_e32 v120, 0x3d372713, v162
	v_add_f32_e32 v145, 1.0, v145
	v_rcp_f32_e32 v174, v145
	v_add_f32_e32 v145, 1.0, v147
	v_mul_f32_e32 v147, 0x3d372713, v127
	v_mul_f32_e32 v147, v127, v147
	v_mul_f32_e32 v149, 0x3d372713, v125
	v_mul_f32_e32 v120, v162, v120
	v_fma_f32 v147, v127, v147, v127
	v_mul_f32_e32 v149, v125, v149
	v_fma_f32 v120, v162, v120, v162
	v_mul_f32_e32 v147, 0x3f4c422a, v147
	v_fma_f32 v149, v125, v149, v125
	v_mul_f32_e32 v120, 0x3f4c422a, v120
	v_mul_f32_e32 v147, 0xc038aa3b, v147
	v_mul_f32_e32 v149, 0x3f4c422a, v149
	v_mul_f32_e32 v120, 0xc038aa3b, v120
	v_mul_f32_e32 v123, 0xc038aa3b, v123
	v_exp_f32_e32 v147, v147
	v_mul_f32_e32 v149, 0xc038aa3b, v149
	v_exp_f32_e32 v120, v120
	v_exp_f32_e32 v123, v123
	v_exp_f32_e32 v149, v149
	v_rcp_f32_e32 v176, v145
	v_add_f32_e32 v145, 1.0, v147
	v_add_f32_e32 v120, 1.0, v120
	v_add_f32_e32 v123, 1.0, v123
	v_rcp_f32_e32 v175, v145
	v_add_f32_e32 v145, 1.0, v149
	v_rcp_f32_e32 v120, v120
	v_rcp_f32_e32 v121, v121
	v_rcp_f32_e32 v177, v145
	v_rcp_f32_e32 v123, v123
	v_pk_mul_f32 v[126:127], v[126:127], v[174:175]
	v_pk_mul_f32 v[162:163], v[162:163], v[120:121]
	v_pk_mul_f32 v[124:125], v[124:125], v[176:177]
	v_pk_mul_f32 v[164:165], v[164:165], v[122:123]
